# final norm phase: gain vector fetched once instead of per row behind full drains; next row's loads issued before the current row's reduction (2 register sets)
# baseline (speedup 1.0000x reference)
; DI void final_phase(const Params& p) {
;     ...
;   for (int tok = blockIdx.x * 4 + wave; tok < TOK; tok += gridDim.x * 4) {
;     float* x = p.out + (size_t)tok * DM;
;     float4 v[4];
;     float ss = 0.f;
; #pragma unroll
;     for (int i = 0; i < 4; i++) {
;       v[i] = *(const float4*)(x + i * 256 + lane * 4);
;       ss += v[i].x * v[i].x + v[i].y * v[i].y + v[i].z * v[i].z + v[i].w * v[i].w;
;     }
.LBB0_1875:
	v_mov_b32_e32 v1, v182
	v_readlane_b32 s2, v254, 4
	v_ashrrev_i32_e32 v0, 6, v182
	s_nop 0
	v_add_u32_e32 v0, s2, v0
	s_movk_i32 s2, 0x4800
	v_cmp_gt_i32_e32 vcc, s2, v0
	s_and_saveexec_b64 s[2:3], vcc
	v_readlane_b32 s8, v254, 47
	v_readlane_b32 s9, v254, 48
	s_cbranch_execz .LBB0_1878
	s_load_dwordx4 s[4:7], s[0:1], 0xe0
	v_lshlrev_b32_e32 v1, 4, v1
	v_mov_b32_e32 v5, 0
	v_and_b32_e32 v4, 0x3f0, v1
	s_mov_b64 s[0:1], 0
	s_waitcnt lgkmcnt(0)
	v_lshl_add_u64 v[2:3], s[4:5], 0, v[4:5]
	v_lshl_add_u64 v[4:5], s[6:7], 0, v[4:5]
	v_mov_b32_e32 v6, 0x358637bd
	s_mov_b32 s2, 0x800000
	s_movk_i32 s3, 0x47ff
	v_ashrrev_i32_e32 v1, 31, v0
	v_lshlrev_b64 v[82:83], 12, v[0:1]
	v_lshl_add_u64 v[28:29], v[4:5], 0, v[82:83]
	global_load_dwordx4 v[8:11], v[28:29], off
	global_load_dwordx4 v[12:15], v[28:29], off offset:1024
	global_load_dwordx4 v[16:19], v[28:29], off offset:2048
	global_load_dwordx4 v[20:23], v[28:29], off offset:3072
	global_load_dwordx4 v[46:49], v[2:3], off
	global_load_dwordx4 v[50:53], v[2:3], off offset:1024
	global_load_dwordx4 v[54:57], v[2:3], off offset:2048
	global_load_dwordx4 v[58:61], v[2:3], off offset:3072
.Lfin_loop:
	v_add_u32_e32 v0, s8, v0
	v_cmp_ge_i32_e32 vcc, s3, v0
	s_mov_b64 s[10:11], vcc
	s_cbranch_vccz .Lfin_nopfA
	v_ashrrev_i32_e32 v1, 31, v0
	v_lshlrev_b64 v[82:83], 12, v[0:1]
	v_lshl_add_u64 v[78:79], v[4:5], 0, v[82:83]
	global_load_dwordx4 v[62:65], v[78:79], off
	global_load_dwordx4 v[66:69], v[78:79], off offset:1024
	global_load_dwordx4 v[70:73], v[78:79], off offset:2048
	global_load_dwordx4 v[74:77], v[78:79], off offset:3072
	s_waitcnt vmcnt(8)
	s_branch .Lfin_goA

; DI void final_phase(const Params& p) {
;     ...
;     float ss = 0.f;
; #pragma unroll
;     for (int i = 0; i < 4; i++) {
;       v[i] = *(const float4*)(x + i * 256 + lane * 4);
;       ss += v[i].x * v[i].x + v[i].y * v[i].y + v[i].z * v[i].z + v[i].w * v[i].w;
;     }
;     ss = wave_sum(ss);
;     const float rstd = rsqrtf(ss * (1.f / 1024.f) + 1e-6f);
; #pragma unroll
;     for (int i = 0; i < 4; i++) {
;       const float4 g = *(const float4*)(p.final_g + i * 256 + lane * 4);
;       *(float4*)(x + i * 256 + lane * 4) = make_float4(v[i].x * rstd * g.x, v[i].y * rstd * g.y, v[i].z * rstd * g.z, v[i].w * rstd * g.w);
;     }
.Lfin_goA:
	v_mov_b32_e32 v32, v9
	v_mov_b32_e32 v33, v13
	v_mov_b32_e32 v30, v8
	v_mov_b32_e32 v31, v12
	v_mov_b32_e32 v40, v17
	v_mov_b32_e32 v41, v21
	v_pk_mul_f32 v[32:33], v[32:33], v[32:33]
	v_mov_b32_e32 v34, v10
	v_mov_b32_e32 v35, v14
	v_mov_b32_e32 v38, v16
	v_mov_b32_e32 v39, v20
	v_pk_mul_f32 v[40:41], v[40:41], v[40:41]
	v_pk_fma_f32 v[30:31], v[30:31], v[30:31], v[32:33]
	v_mov_b32_e32 v36, v11
	v_mov_b32_e32 v37, v15
	v_mov_b32_e32 v42, v18
	v_mov_b32_e32 v43, v22
	v_pk_fma_f32 v[32:33], v[38:39], v[38:39], v[40:41]
	v_pk_fma_f32 v[30:31], v[34:35], v[34:35], v[30:31]
	v_mov_b32_e32 v44, v19
	v_mov_b32_e32 v45, v23
	v_pk_fma_f32 v[32:33], v[42:43], v[42:43], v[32:33]
	v_pk_fma_f32 v[30:31], v[36:37], v[36:37], v[30:31]
	v_pk_fma_f32 v[32:33], v[44:45], v[44:45], v[32:33]
	v_add_f32_e32 v1, v30, v31
	v_add_f32_e32 v1, v1, v32
	v_add_f32_e32 v1, v1, v33
	s_nop 1
	v_add_f32_dpp v1, v1, v1 quad_perm:[1,0,3,2] row_mask:0xf bank_mask:0xf bound_ctrl:1
	s_nop 1
	v_add_f32_dpp v1, v1, v1 quad_perm:[2,3,0,1] row_mask:0xf bank_mask:0xf bound_ctrl:1
	s_nop 1
	v_add_f32_dpp v1, v1, v1 row_half_mirror row_mask:0xf bank_mask:0xf bound_ctrl:1
	s_nop 1
	v_add_f32_dpp v1, v1, v1 row_mirror row_mask:0xf bank_mask:0xf bound_ctrl:1
	s_nop 1
	v_readlane_b32 s6, v1, 16
	v_readlane_b32 s7, v1, 48
	v_readlane_b32 s4, v1, 0
	v_readlane_b32 s5, v1, 32
	v_mov_b32_e32 v30, s6
	v_mov_b32_e32 v31, s7
	v_pk_add_f32 v[30:31], s[4:5], v[30:31]
	s_nop 0
	v_add_f32_e32 v1, v30, v31
	v_fmamk_f32 v1, v1, 0x3a800000, v6
	v_mul_f32_e32 v7, 0x4b800000, v1
	v_cmp_gt_f32_e32 vcc, s2, v1
	s_nop 1
	v_cndmask_b32_e32 v1, v1, v7, vcc
	v_rsq_f32_e32 v1, v1
	s_nop 0
	v_mul_f32_e32 v7, 0x45800000, v1
	v_cndmask_b32_e32 v30, v1, v7, vcc
	s_waitcnt vmcnt(4)
	v_pk_mul_f32 v[8:9], v[8:9], v[30:31] op_sel_hi:[1,0]
	v_pk_mul_f32 v[10:11], v[10:11], v[30:31] op_sel_hi:[1,0]
	v_pk_mul_f32 v[8:9], v[46:47], v[8:9]
	v_pk_mul_f32 v[10:11], v[48:49], v[10:11]
	global_store_dwordx4 v[28:29], v[8:11], off
	v_pk_mul_f32 v[12:13], v[12:13], v[30:31] op_sel_hi:[1,0]
	v_pk_mul_f32 v[14:15], v[14:15], v[30:31] op_sel_hi:[1,0]
	v_pk_mul_f32 v[12:13], v[50:51], v[12:13]
	v_pk_mul_f32 v[14:15], v[52:53], v[14:15]
	global_store_dwordx4 v[28:29], v[12:15], off offset:1024
	v_pk_mul_f32 v[16:17], v[16:17], v[30:31] op_sel_hi:[1,0]
	v_pk_mul_f32 v[18:19], v[18:19], v[30:31] op_sel_hi:[1,0]
	v_pk_mul_f32 v[16:17], v[54:55], v[16:17]
	v_pk_mul_f32 v[18:19], v[56:57], v[18:19]
	global_store_dwordx4 v[28:29], v[16:19], off offset:2048
	v_pk_mul_f32 v[20:21], v[20:21], v[30:31] op_sel_hi:[1,0]
	v_pk_mul_f32 v[22:23], v[22:23], v[30:31] op_sel_hi:[1,0]
	v_pk_mul_f32 v[20:21], v[58:59], v[20:21]
	v_pk_mul_f32 v[22:23], v[60:61], v[22:23]
	global_store_dwordx4 v[28:29], v[20:23], off offset:3072
	s_cmp_lg_u64 s[10:11], 0
	s_cbranch_scc0 .Lfin_done
	v_add_u32_e32 v0, s8, v0
	v_cmp_ge_i32_e32 vcc, s3, v0
	s_mov_b64 s[10:11], vcc
	s_cbranch_vccz .Lfin_nopfB
	v_ashrrev_i32_e32 v1, 31, v0
	v_lshlrev_b64 v[82:83], 12, v[0:1]
	v_lshl_add_u64 v[28:29], v[4:5], 0, v[82:83]
	global_load_dwordx4 v[8:11], v[28:29], off
	global_load_dwordx4 v[12:15], v[28:29], off offset:1024
	global_load_dwordx4 v[16:19], v[28:29], off offset:2048
	global_load_dwordx4 v[20:23], v[28:29], off offset:3072
	s_waitcnt vmcnt(8)
	s_branch .Lfin_goB

; DI void final_phase(const Params& p) {
;     ...
;   for (int tok = blockIdx.x * 4 + wave; tok < TOK; tok += gridDim.x * 4) {
;     float* x = p.out + (size_t)tok * DM;
;     float4 v[4];
;     float ss = 0.f;
; #pragma unroll
;     for (int i = 0; i < 4; i++) {
;       v[i] = *(const float4*)(x + i * 256 + lane * 4);
;       ss += v[i].x * v[i].x + v[i].y * v[i].y + v[i].z * v[i].z + v[i].w * v[i].w;
;     }
;     ss = wave_sum(ss);
;     const float rstd = rsqrtf(ss * (1.f / 1024.f) + 1e-6f);
; #pragma unroll
;     for (int i = 0; i < 4; i++) {
;       const float4 g = *(const float4*)(p.final_g + i * 256 + lane * 4);
;       *(float4*)(x + i * 256 + lane * 4) = make_float4(v[i].x * rstd * g.x, v[i].y * rstd * g.y, v[i].z * rstd * g.z, v[i].w * rstd * g.w);
;     }
;   }
.Lfin_goB:
	v_mov_b32_e32 v32, v63
	v_mov_b32_e32 v33, v67
	v_mov_b32_e32 v30, v62
	v_mov_b32_e32 v31, v66
	v_mov_b32_e32 v40, v71
	v_mov_b32_e32 v41, v75
	v_pk_mul_f32 v[32:33], v[32:33], v[32:33]
	v_mov_b32_e32 v34, v64
	v_mov_b32_e32 v35, v68
	v_mov_b32_e32 v38, v70
	v_mov_b32_e32 v39, v74
	v_pk_mul_f32 v[40:41], v[40:41], v[40:41]
	v_pk_fma_f32 v[30:31], v[30:31], v[30:31], v[32:33]
	v_mov_b32_e32 v36, v65
	v_mov_b32_e32 v37, v69
	v_mov_b32_e32 v42, v72
	v_mov_b32_e32 v43, v76
	v_pk_fma_f32 v[32:33], v[38:39], v[38:39], v[40:41]
	v_pk_fma_f32 v[30:31], v[34:35], v[34:35], v[30:31]
	v_mov_b32_e32 v44, v73
	v_mov_b32_e32 v45, v77
	v_pk_fma_f32 v[32:33], v[42:43], v[42:43], v[32:33]
	v_pk_fma_f32 v[30:31], v[36:37], v[36:37], v[30:31]
	v_pk_fma_f32 v[32:33], v[44:45], v[44:45], v[32:33]
	v_add_f32_e32 v1, v30, v31
	v_add_f32_e32 v1, v1, v32
	v_add_f32_e32 v1, v1, v33
	s_nop 1
	v_add_f32_dpp v1, v1, v1 quad_perm:[1,0,3,2] row_mask:0xf bank_mask:0xf bound_ctrl:1
	s_nop 1
	v_add_f32_dpp v1, v1, v1 quad_perm:[2,3,0,1] row_mask:0xf bank_mask:0xf bound_ctrl:1
	s_nop 1
	v_add_f32_dpp v1, v1, v1 row_half_mirror row_mask:0xf bank_mask:0xf bound_ctrl:1
	s_nop 1
	v_add_f32_dpp v1, v1, v1 row_mirror row_mask:0xf bank_mask:0xf bound_ctrl:1
	s_nop 1
	v_readlane_b32 s6, v1, 16
	v_readlane_b32 s7, v1, 48
	v_readlane_b32 s4, v1, 0
	v_readlane_b32 s5, v1, 32
	v_mov_b32_e32 v30, s6
	v_mov_b32_e32 v31, s7
	v_pk_add_f32 v[30:31], s[4:5], v[30:31]
	s_nop 0
	v_add_f32_e32 v1, v30, v31
	v_fmamk_f32 v1, v1, 0x3a800000, v6
	v_mul_f32_e32 v7, 0x4b800000, v1
	v_cmp_gt_f32_e32 vcc, s2, v1
	s_nop 1
	v_cndmask_b32_e32 v1, v1, v7, vcc
	v_rsq_f32_e32 v1, v1
	s_nop 0
	v_mul_f32_e32 v7, 0x45800000, v1
	v_cndmask_b32_e32 v30, v1, v7, vcc
	s_waitcnt vmcnt(4)
	v_pk_mul_f32 v[62:63], v[62:63], v[30:31] op_sel_hi:[1,0]
	v_pk_mul_f32 v[64:65], v[64:65], v[30:31] op_sel_hi:[1,0]
	v_pk_mul_f32 v[62:63], v[46:47], v[62:63]
	v_pk_mul_f32 v[64:65], v[48:49], v[64:65]
	global_store_dwordx4 v[78:79], v[62:65], off
	v_pk_mul_f32 v[66:67], v[66:67], v[30:31] op_sel_hi:[1,0]
	v_pk_mul_f32 v[68:69], v[68:69], v[30:31] op_sel_hi:[1,0]
	v_pk_mul_f32 v[66:67], v[50:51], v[66:67]
	v_pk_mul_f32 v[68:69], v[52:53], v[68:69]
	global_store_dwordx4 v[78:79], v[66:69], off offset:1024
	v_pk_mul_f32 v[70:71], v[70:71], v[30:31] op_sel_hi:[1,0]
	v_pk_mul_f32 v[72:73], v[72:73], v[30:31] op_sel_hi:[1,0]
	v_pk_mul_f32 v[70:71], v[54:55], v[70:71]
	v_pk_mul_f32 v[72:73], v[56:57], v[72:73]
	global_store_dwordx4 v[78:79], v[70:73], off offset:2048
	v_pk_mul_f32 v[74:75], v[74:75], v[30:31] op_sel_hi:[1,0]
	v_pk_mul_f32 v[76:77], v[76:77], v[30:31] op_sel_hi:[1,0]
	v_pk_mul_f32 v[74:75], v[58:59], v[74:75]
	v_pk_mul_f32 v[76:77], v[60:61], v[76:77]
	global_store_dwordx4 v[78:79], v[74:77], off offset:3072
	s_cmp_lg_u64 s[10:11], 0
	s_cbranch_scc0 .Lfin_done
	s_branch .Lfin_loop
.Lfin_done:
.LBB0_1878:
	s_endpgm
